# down-projection epilogue rewritten by hand: lanes re-paired (DPP row_ror:8) so every 16-byte load/store covers full 128-byte lines; 8 row pieces in flight with counted waits
# speedup vs baseline: 1.0494x; 1.0034x over previous
; #define PG8_LAS __attribute__((address_space(3)))
;     __device__ __forceinline__ void fused(f32x4 (&acc)[2][2][4][2], const Unit& u, int wr, int wc, int fr, int fq, PG8_LAS unsigned char* lds, int wid, int lane) const {
;         const PG8_LAS float* S = (const PG8_LAS float*)(lds + 4096);
;         const int col0 = u.pn * BM + wc * 32 + 4 * fq;
;         st.run(acc, u, wr, wc, fr, fq, lds, wid, lane);
;         f32x4 g[2][2];
; #pragma unroll
;         for (int bj = 0; bj < 2; ++bj)
; #pragma unroll
;             for (int n = 0; n < 2; ++n) g[bj][n] = *(const f32x4*)(gv + col0 + bj * HALF + n * 16);
; #pragma unroll
;         for (int ai = 0; ai < 2; ++ai)
; #pragma unroll
;             for (int m = 0; m < 4; ++m) { const int r = ai * HALF + wr * 64 + m * 16 + fr; const float rs = S[r]; const size_t off = (size_t)(row_off + u.pm * BM + r) * DM + col0;
; #pragma unroll
;                 for (int bj = 0; bj < 2; ++bj)
; #pragma unroll
;                     for (int n = 0; n < 2; ++n) { const f32x4 bs = *(const f32x4*)(base + off + bj * HALF + n * 16); __builtin_nontemporal_store(bs + acc[ai][bj][m][n] * rs * g[bj][n], (f32x4*)(out + off + bj * HALF + n * 16)); }
;                 if (m & 1) asm volatile("" ::: "memory"); }
;         asm volatile("s_waitcnt lgkmcnt(0)" ::: "memory"); __builtin_amdgcn_s_barrier(); asm volatile("" ::: "memory");
.LBB0_1113:
	s_or_b64 exec, exec, s[10:11]
	s_lshl_b32 s6, s50, 12
	s_add_i32 s6, s51, s6
	s_ashr_i32 s7, s6, 31
	s_lshl_b64 s[6:7], s[6:7], 2
	s_add_u32 s6, s14, s6
	s_addc_u32 s7, s15, s7
	s_lshl_b32 s9, s16, 5
	s_lshl_b32 s10, s24, 8
	v_lshrrev_b32_e32 v128, 2, v138
	s_or_b32 s9, s10, s9
	v_and_or_b32 v128, v128, 12, s9
	s_waitcnt lgkmcnt(0)
	v_ashrrev_i32_e32 v129, 31, v128
	v_lshlrev_b64 v[150:151], 2, v[128:129]
	s_lshl_b32 s8, s50, 14
	v_lshl_add_u64 v[128:129], s[6:7], 0, v[150:151]
	s_lshl_b32 s6, s53, 8
	s_add_i32 s6, s6, s8
	v_add_u32_e32 v152, s6, v157
	v_ashrrev_i32_e32 v153, 31, v152
	v_lshl_add_u64 v[140:141], v[128:129], 0, s[22:23]
	v_add_co_u32_e32 v128, vcc, s49, v128
	v_lshlrev_b64 v[132:133], 12, v[152:153]
	v_add_u32_e32 v174, 16, v152
	s_waitcnt lgkmcnt(0)
	s_barrier
	s_mov_b32 s7, 0
	s_lshl_b64 s[6:7], s[6:7], 12
	s_add_u32 s6, s12, s6
	s_addc_u32 s7, s13, s7
	v_and_b32_e32 v136, 8, v157
	v_sub_u32_e32 v157, v157, v136
	v_lshlrev_b32_e32 v137, 3, v136
	v_lshl_add_u32 v144, v157, 2, 0
	v_add_u32_e32 v144, 0x1000, v144
	v_lshl_add_u32 v157, v157, 12, v150
	v_add_u32_e32 v157, v157, v137
	v_add_co_u32_e32 v140, vcc, v137, v140
	s_nop 1
	v_addc_co_u32_e32 v141, vcc, 0, v141, vcc
	global_load_dwordx4 v[128:131], v[140:141], off
	global_load_dwordx4 v[132:135], v[140:141], off offset:512
	ds_read2_b32 v[228:229], v144 offset0:0 offset1:8
	ds_read2_b32 v[230:231], v144 offset0:16 offset1:24
	ds_read2_b32 v[232:233], v144 offset0:32 offset1:40
	ds_read2_b32 v[234:235], v144 offset0:48 offset1:56
	ds_read2_b32 v[236:237], v144 offset0:128 offset1:136
	ds_read2_b32 v[238:239], v144 offset0:144 offset1:152
	ds_read2_b32 v[240:241], v144 offset0:160 offset1:168
	ds_read2_b32 v[242:243], v144 offset0:176 offset1:184
	v_mov_b32_e32 v252, v157
	v_add_u32_e32 v253, 0x8000, v157
	global_load_dwordx4 v[158:161], v252, s[6:7]
	global_load_dwordx4 v[162:165], v253, s[6:7]
	v_mov_b32_e32 v252, v157
	v_add_u32_e32 v253, 0x8000, v157
	global_load_dwordx4 v[166:169], v252, s[6:7] offset:512
	global_load_dwordx4 v[170:173], v253, s[6:7] offset:512
	v_add_u32_e32 v252, 0x10000, v157
	v_add_u32_e32 v253, 0x18000, v157
	global_load_dwordx4 v[174:177], v252, s[6:7]
	global_load_dwordx4 v[178:181], v253, s[6:7]
	v_add_u32_e32 v252, 0x10000, v157
	v_add_u32_e32 v253, 0x18000, v157
	global_load_dwordx4 v[182:185], v252, s[6:7] offset:512
	global_load_dwordx4 v[186:189], v253, s[6:7] offset:512
	v_add_u32_e32 v252, 0x20000, v157
	v_add_u32_e32 v253, 0x28000, v157
	global_load_dwordx4 v[196:199], v252, s[6:7]
	global_load_dwordx4 v[200:203], v253, s[6:7]
	v_add_u32_e32 v252, 0x20000, v157
	v_add_u32_e32 v253, 0x28000, v157
	global_load_dwordx4 v[204:207], v252, s[6:7] offset:512
	global_load_dwordx4 v[208:211], v253, s[6:7] offset:512
	v_add_u32_e32 v252, 0x30000, v157
	v_add_u32_e32 v253, 0x38000, v157
	global_load_dwordx4 v[212:215], v252, s[6:7]
	global_load_dwordx4 v[216:219], v253, s[6:7]
	v_add_u32_e32 v252, 0x30000, v157
	v_add_u32_e32 v253, 0x38000, v157
	global_load_dwordx4 v[220:223], v252, s[6:7] offset:512
	global_load_dwordx4 v[224:227], v253, s[6:7] offset:512
	s_waitcnt lgkmcnt(0)
	v_mov_b32_e32 v190, v124
	v_mov_b32_e32 v191, v125
	v_mov_b32_e32 v192, v126
	v_mov_b32_e32 v193, v127
	v_mov_b32_dpp v124, v120 row_ror:8 row_mask:0xf bank_mask:0xc
	v_mov_b32_dpp v125, v121 row_ror:8 row_mask:0xf bank_mask:0xc
	v_mov_b32_dpp v126, v122 row_ror:8 row_mask:0xf bank_mask:0xc
	v_mov_b32_dpp v127, v123 row_ror:8 row_mask:0xf bank_mask:0xc
	v_mov_b32_dpp v120, v190 row_ror:8 row_mask:0xf bank_mask:0x3
	v_mov_b32_dpp v121, v191 row_ror:8 row_mask:0xf bank_mask:0x3
	v_mov_b32_dpp v122, v192 row_ror:8 row_mask:0xf bank_mask:0x3
	v_mov_b32_dpp v123, v193 row_ror:8 row_mask:0xf bank_mask:0x3
	s_waitcnt vmcnt(14)
	v_mul_f32_e32 v124, v124, v228
	v_mul_f32_e32 v125, v125, v228
	v_mul_f32_e32 v126, v126, v228
	v_mul_f32_e32 v127, v127, v228
	v_mul_f32_e32 v120, v120, v229
	v_mul_f32_e32 v121, v121, v229
	v_mul_f32_e32 v122, v122, v229
	v_mul_f32_e32 v123, v123, v229
	v_fma_f32 v124, v124, v128, v158
	v_fma_f32 v125, v125, v129, v159
	v_fma_f32 v126, v126, v130, v160
	v_fma_f32 v127, v127, v131, v161
	v_fma_f32 v120, v120, v128, v162
	v_fma_f32 v121, v121, v129, v163
	v_fma_f32 v122, v122, v130, v164
	v_fma_f32 v123, v123, v131, v165
	v_mov_b32_e32 v252, v157
	v_add_u32_e32 v253, 0x8000, v157
	global_store_dwordx4 v252, v[124:127], s[6:7] nt
	global_store_dwordx4 v253, v[120:123], s[6:7] nt
	v_add_u32_e32 v252, 0x80000, v157
	v_add_u32_e32 v253, 0x88000, v157
	global_load_dwordx4 v[158:161], v252, s[6:7]
	global_load_dwordx4 v[162:165], v253, s[6:7]
	v_mov_b32_e32 v190, v108
	v_mov_b32_e32 v191, v109
	v_mov_b32_e32 v192, v110
	v_mov_b32_e32 v193, v111
	v_mov_b32_dpp v108, v104 row_ror:8 row_mask:0xf bank_mask:0xc
	v_mov_b32_dpp v109, v105 row_ror:8 row_mask:0xf bank_mask:0xc
	v_mov_b32_dpp v110, v106 row_ror:8 row_mask:0xf bank_mask:0xc
	v_mov_b32_dpp v111, v107 row_ror:8 row_mask:0xf bank_mask:0xc
	v_mov_b32_dpp v104, v190 row_ror:8 row_mask:0xf bank_mask:0x3
	v_mov_b32_dpp v105, v191 row_ror:8 row_mask:0xf bank_mask:0x3
	v_mov_b32_dpp v106, v192 row_ror:8 row_mask:0xf bank_mask:0x3
	v_mov_b32_dpp v107, v193 row_ror:8 row_mask:0xf bank_mask:0x3
	s_waitcnt vmcnt(16)
;     __device__ __forceinline__ void fused(f32x4 (&acc)[2][2][4][2], const Unit& u, int wr, int wc, int fr, int fq, PG8_LAS unsigned char* lds, int wid, int lane) const {
;     ...
; #pragma unroll
;         for (int ai = 0; ai < 2; ++ai)
; #pragma unroll
;             for (int m = 0; m < 4; ++m) { const int r = ai * HALF + wr * 64 + m * 16 + fr; const float rs = S[r]; const size_t off = (size_t)(row_off + u.pm * BM + r) * DM + col0;
; #pragma unroll
;                 for (int bj = 0; bj < 2; ++bj)
; #pragma unroll
;                     for (int n = 0; n < 2; ++n) { const f32x4 bs = *(const f32x4*)(base + off + bj * HALF + n * 16); __builtin_nontemporal_store(bs + acc[ai][bj][m][n] * rs * g[bj][n], (f32x4*)(out + off + bj * HALF + n * 16)); }
;                 if (m & 1) asm volatile("" ::: "memory"); }
	v_mul_f32_e32 v108, v108, v228
	v_mul_f32_e32 v109, v109, v228
	v_mul_f32_e32 v110, v110, v228
	v_mul_f32_e32 v111, v111, v228
	v_mul_f32_e32 v104, v104, v229
	v_mul_f32_e32 v105, v105, v229
	v_mul_f32_e32 v106, v106, v229
	v_mul_f32_e32 v107, v107, v229
	v_fma_f32 v108, v108, v132, v166
	v_fma_f32 v109, v109, v133, v167
	v_fma_f32 v110, v110, v134, v168
	v_fma_f32 v111, v111, v135, v169
	v_fma_f32 v104, v104, v132, v170
	v_fma_f32 v105, v105, v133, v171
	v_fma_f32 v106, v106, v134, v172
	v_fma_f32 v107, v107, v135, v173
	v_mov_b32_e32 v252, v157
	v_add_u32_e32 v253, 0x8000, v157
	global_store_dwordx4 v252, v[108:111], s[6:7] offset:512 nt
	global_store_dwordx4 v253, v[104:107], s[6:7] offset:512 nt
	v_add_u32_e32 v252, 0x80000, v157
	v_add_u32_e32 v253, 0x88000, v157
	global_load_dwordx4 v[166:169], v252, s[6:7] offset:512
	global_load_dwordx4 v[170:173], v253, s[6:7] offset:512
	v_mov_b32_e32 v190, v116
	v_mov_b32_e32 v191, v117
	v_mov_b32_e32 v192, v118
	v_mov_b32_e32 v193, v119
	v_mov_b32_dpp v116, v112 row_ror:8 row_mask:0xf bank_mask:0xc
	v_mov_b32_dpp v117, v113 row_ror:8 row_mask:0xf bank_mask:0xc
	v_mov_b32_dpp v118, v114 row_ror:8 row_mask:0xf bank_mask:0xc
	v_mov_b32_dpp v119, v115 row_ror:8 row_mask:0xf bank_mask:0xc
	v_mov_b32_dpp v112, v190 row_ror:8 row_mask:0xf bank_mask:0x3
	v_mov_b32_dpp v113, v191 row_ror:8 row_mask:0xf bank_mask:0x3
	v_mov_b32_dpp v114, v192 row_ror:8 row_mask:0xf bank_mask:0x3
	v_mov_b32_dpp v115, v193 row_ror:8 row_mask:0xf bank_mask:0x3
	s_waitcnt vmcnt(18)
	v_mul_f32_e32 v116, v116, v230
	v_mul_f32_e32 v117, v117, v230
	v_mul_f32_e32 v118, v118, v230
	v_mul_f32_e32 v119, v119, v230
	v_mul_f32_e32 v112, v112, v231
	v_mul_f32_e32 v113, v113, v231
	v_mul_f32_e32 v114, v114, v231
	v_mul_f32_e32 v115, v115, v231
	v_fma_f32 v116, v116, v128, v174
	v_fma_f32 v117, v117, v129, v175
	v_fma_f32 v118, v118, v130, v176
	v_fma_f32 v119, v119, v131, v177
	v_fma_f32 v112, v112, v128, v178
	v_fma_f32 v113, v113, v129, v179
	v_fma_f32 v114, v114, v130, v180
	v_fma_f32 v115, v115, v131, v181
	v_add_u32_e32 v252, 0x10000, v157
	v_add_u32_e32 v253, 0x18000, v157
	global_store_dwordx4 v252, v[116:119], s[6:7] nt
	global_store_dwordx4 v253, v[112:115], s[6:7] nt
	v_add_u32_e32 v252, 0x90000, v157
	v_add_u32_e32 v253, 0x98000, v157
	global_load_dwordx4 v[174:177], v252, s[6:7]
	global_load_dwordx4 v[178:181], v253, s[6:7]
	v_mov_b32_e32 v190, v100
	v_mov_b32_e32 v191, v101
	v_mov_b32_e32 v192, v102
	v_mov_b32_e32 v193, v103
	v_mov_b32_dpp v100, v96 row_ror:8 row_mask:0xf bank_mask:0xc
	v_mov_b32_dpp v101, v97 row_ror:8 row_mask:0xf bank_mask:0xc
	v_mov_b32_dpp v102, v98 row_ror:8 row_mask:0xf bank_mask:0xc
	v_mov_b32_dpp v103, v99 row_ror:8 row_mask:0xf bank_mask:0xc
	v_mov_b32_dpp v96, v190 row_ror:8 row_mask:0xf bank_mask:0x3
	v_mov_b32_dpp v97, v191 row_ror:8 row_mask:0xf bank_mask:0x3
	v_mov_b32_dpp v98, v192 row_ror:8 row_mask:0xf bank_mask:0x3
	v_mov_b32_dpp v99, v193 row_ror:8 row_mask:0xf bank_mask:0x3
	s_waitcnt vmcnt(20)
	v_mul_f32_e32 v100, v100, v230
	v_mul_f32_e32 v101, v101, v230
	v_mul_f32_e32 v102, v102, v230
	v_mul_f32_e32 v103, v103, v230
	v_mul_f32_e32 v96, v96, v231
	v_mul_f32_e32 v97, v97, v231
	v_mul_f32_e32 v98, v98, v231
	v_mul_f32_e32 v99, v99, v231
	v_fma_f32 v100, v100, v132, v182
	v_fma_f32 v101, v101, v133, v183
	v_fma_f32 v102, v102, v134, v184
	v_fma_f32 v103, v103, v135, v185
	v_fma_f32 v96, v96, v132, v186
	v_fma_f32 v97, v97, v133, v187
	v_fma_f32 v98, v98, v134, v188
	v_fma_f32 v99, v99, v135, v189
	v_add_u32_e32 v252, 0x10000, v157
	v_add_u32_e32 v253, 0x18000, v157
	global_store_dwordx4 v252, v[100:103], s[6:7] offset:512 nt
	global_store_dwordx4 v253, v[96:99], s[6:7] offset:512 nt
	v_add_u32_e32 v252, 0x90000, v157
	v_add_u32_e32 v253, 0x98000, v157
	global_load_dwordx4 v[182:185], v252, s[6:7] offset:512
	global_load_dwordx4 v[186:189], v253, s[6:7] offset:512
	v_mov_b32_e32 v190, v92
	v_mov_b32_e32 v191, v93
	v_mov_b32_e32 v192, v94
	v_mov_b32_e32 v193, v95
	v_mov_b32_dpp v92, v88 row_ror:8 row_mask:0xf bank_mask:0xc
	v_mov_b32_dpp v93, v89 row_ror:8 row_mask:0xf bank_mask:0xc
	v_mov_b32_dpp v94, v90 row_ror:8 row_mask:0xf bank_mask:0xc
	v_mov_b32_dpp v95, v91 row_ror:8 row_mask:0xf bank_mask:0xc
	v_mov_b32_dpp v88, v190 row_ror:8 row_mask:0xf bank_mask:0x3
	v_mov_b32_dpp v89, v191 row_ror:8 row_mask:0xf bank_mask:0x3
	v_mov_b32_dpp v90, v192 row_ror:8 row_mask:0xf bank_mask:0x3
	v_mov_b32_dpp v91, v193 row_ror:8 row_mask:0xf bank_mask:0x3
	s_waitcnt vmcnt(22)
	v_mul_f32_e32 v92, v92, v232
	v_mul_f32_e32 v93, v93, v232
	v_mul_f32_e32 v94, v94, v232
	v_mul_f32_e32 v95, v95, v232
	v_mul_f32_e32 v88, v88, v233
	v_mul_f32_e32 v89, v89, v233
	v_mul_f32_e32 v90, v90, v233
	v_mul_f32_e32 v91, v91, v233
	v_fma_f32 v92, v92, v128, v196
	v_fma_f32 v93, v93, v129, v197
	v_fma_f32 v94, v94, v130, v198
	v_fma_f32 v95, v95, v131, v199
	v_fma_f32 v88, v88, v128, v200
	v_fma_f32 v89, v89, v129, v201
	v_fma_f32 v90, v90, v130, v202
	v_fma_f32 v91, v91, v131, v203
	v_add_u32_e32 v252, 0x20000, v157
	v_add_u32_e32 v253, 0x28000, v157
	global_store_dwordx4 v252, v[92:95], s[6:7] nt
	global_store_dwordx4 v253, v[88:91], s[6:7] nt
	v_add_u32_e32 v252, 0xa0000, v157
	v_add_u32_e32 v253, 0xa8000, v157
	global_load_dwordx4 v[196:199], v252, s[6:7]
	global_load_dwordx4 v[200:203], v253, s[6:7]
	v_mov_b32_e32 v190, v76
	v_mov_b32_e32 v191, v77
	v_mov_b32_e32 v192, v78
	v_mov_b32_e32 v193, v79
	v_mov_b32_dpp v76, v72 row_ror:8 row_mask:0xf bank_mask:0xc
	v_mov_b32_dpp v77, v73 row_ror:8 row_mask:0xf bank_mask:0xc
	v_mov_b32_dpp v78, v74 row_ror:8 row_mask:0xf bank_mask:0xc
	v_mov_b32_dpp v79, v75 row_ror:8 row_mask:0xf bank_mask:0xc
	v_mov_b32_dpp v72, v190 row_ror:8 row_mask:0xf bank_mask:0x3
	v_mov_b32_dpp v73, v191 row_ror:8 row_mask:0xf bank_mask:0x3
	v_mov_b32_dpp v74, v192 row_ror:8 row_mask:0xf bank_mask:0x3
	v_mov_b32_dpp v75, v193 row_ror:8 row_mask:0xf bank_mask:0x3
	s_waitcnt vmcnt(24)
;     __device__ __forceinline__ void fused(f32x4 (&acc)[2][2][4][2], const Unit& u, int wr, int wc, int fr, int fq, PG8_LAS unsigned char* lds, int wid, int lane) const {
;     ...
; #pragma unroll
;         for (int ai = 0; ai < 2; ++ai)
; #pragma unroll
;             for (int m = 0; m < 4; ++m) { const int r = ai * HALF + wr * 64 + m * 16 + fr; const float rs = S[r]; const size_t off = (size_t)(row_off + u.pm * BM + r) * DM + col0;
; #pragma unroll
;                 for (int bj = 0; bj < 2; ++bj)
; #pragma unroll
;                     for (int n = 0; n < 2; ++n) { const f32x4 bs = *(const f32x4*)(base + off + bj * HALF + n * 16); __builtin_nontemporal_store(bs + acc[ai][bj][m][n] * rs * g[bj][n], (f32x4*)(out + off + bj * HALF + n * 16)); }
;                 if (m & 1) asm volatile("" ::: "memory"); }
	v_mul_f32_e32 v76, v76, v232
	v_mul_f32_e32 v77, v77, v232
	v_mul_f32_e32 v78, v78, v232
	v_mul_f32_e32 v79, v79, v232
	v_mul_f32_e32 v72, v72, v233
	v_mul_f32_e32 v73, v73, v233
	v_mul_f32_e32 v74, v74, v233
	v_mul_f32_e32 v75, v75, v233
	v_fma_f32 v76, v76, v132, v204
	v_fma_f32 v77, v77, v133, v205
	v_fma_f32 v78, v78, v134, v206
	v_fma_f32 v79, v79, v135, v207
	v_fma_f32 v72, v72, v132, v208
	v_fma_f32 v73, v73, v133, v209
	v_fma_f32 v74, v74, v134, v210
	v_fma_f32 v75, v75, v135, v211
	v_add_u32_e32 v252, 0x20000, v157
	v_add_u32_e32 v253, 0x28000, v157
	global_store_dwordx4 v252, v[76:79], s[6:7] offset:512 nt
	global_store_dwordx4 v253, v[72:75], s[6:7] offset:512 nt
	v_add_u32_e32 v252, 0xa0000, v157
	v_add_u32_e32 v253, 0xa8000, v157
	global_load_dwordx4 v[204:207], v252, s[6:7] offset:512
	global_load_dwordx4 v[208:211], v253, s[6:7] offset:512
	v_mov_b32_e32 v190, v84
	v_mov_b32_e32 v191, v85
	v_mov_b32_e32 v192, v86
	v_mov_b32_e32 v193, v87
	v_mov_b32_dpp v84, v80 row_ror:8 row_mask:0xf bank_mask:0xc
	v_mov_b32_dpp v85, v81 row_ror:8 row_mask:0xf bank_mask:0xc
	v_mov_b32_dpp v86, v82 row_ror:8 row_mask:0xf bank_mask:0xc
	v_mov_b32_dpp v87, v83 row_ror:8 row_mask:0xf bank_mask:0xc
	v_mov_b32_dpp v80, v190 row_ror:8 row_mask:0xf bank_mask:0x3
	v_mov_b32_dpp v81, v191 row_ror:8 row_mask:0xf bank_mask:0x3
	v_mov_b32_dpp v82, v192 row_ror:8 row_mask:0xf bank_mask:0x3
	v_mov_b32_dpp v83, v193 row_ror:8 row_mask:0xf bank_mask:0x3
	s_waitcnt vmcnt(26)
	v_mul_f32_e32 v84, v84, v234
	v_mul_f32_e32 v85, v85, v234
	v_mul_f32_e32 v86, v86, v234
	v_mul_f32_e32 v87, v87, v234
	v_mul_f32_e32 v80, v80, v235
	v_mul_f32_e32 v81, v81, v235
	v_mul_f32_e32 v82, v82, v235
	v_mul_f32_e32 v83, v83, v235
	v_fma_f32 v84, v84, v128, v212
	v_fma_f32 v85, v85, v129, v213
	v_fma_f32 v86, v86, v130, v214
	v_fma_f32 v87, v87, v131, v215
	v_fma_f32 v80, v80, v128, v216
	v_fma_f32 v81, v81, v129, v217
	v_fma_f32 v82, v82, v130, v218
	v_fma_f32 v83, v83, v131, v219
	v_add_u32_e32 v252, 0x30000, v157
	v_add_u32_e32 v253, 0x38000, v157
	global_store_dwordx4 v252, v[84:87], s[6:7] nt
	global_store_dwordx4 v253, v[80:83], s[6:7] nt
	v_add_u32_e32 v252, 0xb0000, v157
	v_add_u32_e32 v253, 0xb8000, v157
	global_load_dwordx4 v[212:215], v252, s[6:7]
	global_load_dwordx4 v[216:219], v253, s[6:7]
	v_mov_b32_e32 v190, v68
	v_mov_b32_e32 v191, v69
	v_mov_b32_e32 v192, v70
	v_mov_b32_e32 v193, v71
	v_mov_b32_dpp v68, v64 row_ror:8 row_mask:0xf bank_mask:0xc
	v_mov_b32_dpp v69, v65 row_ror:8 row_mask:0xf bank_mask:0xc
	v_mov_b32_dpp v70, v66 row_ror:8 row_mask:0xf bank_mask:0xc
	v_mov_b32_dpp v71, v67 row_ror:8 row_mask:0xf bank_mask:0xc
	v_mov_b32_dpp v64, v190 row_ror:8 row_mask:0xf bank_mask:0x3
	v_mov_b32_dpp v65, v191 row_ror:8 row_mask:0xf bank_mask:0x3
	v_mov_b32_dpp v66, v192 row_ror:8 row_mask:0xf bank_mask:0x3
	v_mov_b32_dpp v67, v193 row_ror:8 row_mask:0xf bank_mask:0x3
	s_waitcnt vmcnt(28)
	v_mul_f32_e32 v68, v68, v234
	v_mul_f32_e32 v69, v69, v234
	v_mul_f32_e32 v70, v70, v234
	v_mul_f32_e32 v71, v71, v234
	v_mul_f32_e32 v64, v64, v235
	v_mul_f32_e32 v65, v65, v235
	v_mul_f32_e32 v66, v66, v235
	v_mul_f32_e32 v67, v67, v235
	v_fma_f32 v68, v68, v132, v220
	v_fma_f32 v69, v69, v133, v221
	v_fma_f32 v70, v70, v134, v222
	v_fma_f32 v71, v71, v135, v223
	v_fma_f32 v64, v64, v132, v224
	v_fma_f32 v65, v65, v133, v225
	v_fma_f32 v66, v66, v134, v226
	v_fma_f32 v67, v67, v135, v227
	v_add_u32_e32 v252, 0x30000, v157
	v_add_u32_e32 v253, 0x38000, v157
	global_store_dwordx4 v252, v[68:71], s[6:7] offset:512 nt
	global_store_dwordx4 v253, v[64:67], s[6:7] offset:512 nt
	v_add_u32_e32 v252, 0xb0000, v157
	v_add_u32_e32 v253, 0xb8000, v157
	global_load_dwordx4 v[220:223], v252, s[6:7] offset:512
	global_load_dwordx4 v[224:227], v253, s[6:7] offset:512
	v_mov_b32_e32 v190, v60
	v_mov_b32_e32 v191, v61
	v_mov_b32_e32 v192, v62
	v_mov_b32_e32 v193, v63
	v_mov_b32_dpp v60, v56 row_ror:8 row_mask:0xf bank_mask:0xc
	v_mov_b32_dpp v61, v57 row_ror:8 row_mask:0xf bank_mask:0xc
	v_mov_b32_dpp v62, v58 row_ror:8 row_mask:0xf bank_mask:0xc
	v_mov_b32_dpp v63, v59 row_ror:8 row_mask:0xf bank_mask:0xc
	v_mov_b32_dpp v56, v190 row_ror:8 row_mask:0xf bank_mask:0x3
	v_mov_b32_dpp v57, v191 row_ror:8 row_mask:0xf bank_mask:0x3
	v_mov_b32_dpp v58, v192 row_ror:8 row_mask:0xf bank_mask:0x3
	v_mov_b32_dpp v59, v193 row_ror:8 row_mask:0xf bank_mask:0x3
	s_waitcnt vmcnt(28)
	v_mul_f32_e32 v60, v60, v236
	v_mul_f32_e32 v61, v61, v236
	v_mul_f32_e32 v62, v62, v236
	v_mul_f32_e32 v63, v63, v236
	v_mul_f32_e32 v56, v56, v237
	v_mul_f32_e32 v57, v57, v237
	v_mul_f32_e32 v58, v58, v237
	v_mul_f32_e32 v59, v59, v237
	v_fma_f32 v60, v60, v128, v158
	v_fma_f32 v61, v61, v129, v159
	v_fma_f32 v62, v62, v130, v160
	v_fma_f32 v63, v63, v131, v161
	v_fma_f32 v56, v56, v128, v162
	v_fma_f32 v57, v57, v129, v163
	v_fma_f32 v58, v58, v130, v164
	v_fma_f32 v59, v59, v131, v165
	v_add_u32_e32 v252, 0x80000, v157
	v_add_u32_e32 v253, 0x88000, v157
	global_store_dwordx4 v252, v[60:63], s[6:7] nt
	global_store_dwordx4 v253, v[56:59], s[6:7] nt
	v_mov_b32_e32 v190, v44
	v_mov_b32_e32 v191, v45
	v_mov_b32_e32 v192, v46
	v_mov_b32_e32 v193, v47
	v_mov_b32_dpp v44, v40 row_ror:8 row_mask:0xf bank_mask:0xc
	v_mov_b32_dpp v45, v41 row_ror:8 row_mask:0xf bank_mask:0xc
	v_mov_b32_dpp v46, v42 row_ror:8 row_mask:0xf bank_mask:0xc
	v_mov_b32_dpp v47, v43 row_ror:8 row_mask:0xf bank_mask:0xc
	v_mov_b32_dpp v40, v190 row_ror:8 row_mask:0xf bank_mask:0x3
	v_mov_b32_dpp v41, v191 row_ror:8 row_mask:0xf bank_mask:0x3
	v_mov_b32_dpp v42, v192 row_ror:8 row_mask:0xf bank_mask:0x3
	v_mov_b32_dpp v43, v193 row_ror:8 row_mask:0xf bank_mask:0x3
	s_waitcnt vmcnt(26)
;     __device__ __forceinline__ void fused(f32x4 (&acc)[2][2][4][2], const Unit& u, int wr, int wc, int fr, int fq, PG8_LAS unsigned char* lds, int wid, int lane) const {
;     ...
; #pragma unroll
;         for (int ai = 0; ai < 2; ++ai)
; #pragma unroll
;             for (int m = 0; m < 4; ++m) { const int r = ai * HALF + wr * 64 + m * 16 + fr; const float rs = S[r]; const size_t off = (size_t)(row_off + u.pm * BM + r) * DM + col0;
; #pragma unroll
;                 for (int bj = 0; bj < 2; ++bj)
; #pragma unroll
;                     for (int n = 0; n < 2; ++n) { const f32x4 bs = *(const f32x4*)(base + off + bj * HALF + n * 16); __builtin_nontemporal_store(bs + acc[ai][bj][m][n] * rs * g[bj][n], (f32x4*)(out + off + bj * HALF + n * 16)); }
;                 if (m & 1) asm volatile("" ::: "memory"); }
	v_mul_f32_e32 v44, v44, v236
	v_mul_f32_e32 v45, v45, v236
	v_mul_f32_e32 v46, v46, v236
	v_mul_f32_e32 v47, v47, v236
	v_mul_f32_e32 v40, v40, v237
	v_mul_f32_e32 v41, v41, v237
	v_mul_f32_e32 v42, v42, v237
	v_mul_f32_e32 v43, v43, v237
	v_fma_f32 v44, v44, v132, v166
	v_fma_f32 v45, v45, v133, v167
	v_fma_f32 v46, v46, v134, v168
	v_fma_f32 v47, v47, v135, v169
	v_fma_f32 v40, v40, v132, v170
	v_fma_f32 v41, v41, v133, v171
	v_fma_f32 v42, v42, v134, v172
	v_fma_f32 v43, v43, v135, v173
	v_add_u32_e32 v252, 0x80000, v157
	v_add_u32_e32 v253, 0x88000, v157
	global_store_dwordx4 v252, v[44:47], s[6:7] offset:512 nt
	global_store_dwordx4 v253, v[40:43], s[6:7] offset:512 nt
	v_mov_b32_e32 v190, v52
	v_mov_b32_e32 v191, v53
	v_mov_b32_e32 v192, v54
	v_mov_b32_e32 v193, v55
	v_mov_b32_dpp v52, v48 row_ror:8 row_mask:0xf bank_mask:0xc
	v_mov_b32_dpp v53, v49 row_ror:8 row_mask:0xf bank_mask:0xc
	v_mov_b32_dpp v54, v50 row_ror:8 row_mask:0xf bank_mask:0xc
	v_mov_b32_dpp v55, v51 row_ror:8 row_mask:0xf bank_mask:0xc
	v_mov_b32_dpp v48, v190 row_ror:8 row_mask:0xf bank_mask:0x3
	v_mov_b32_dpp v49, v191 row_ror:8 row_mask:0xf bank_mask:0x3
	v_mov_b32_dpp v50, v192 row_ror:8 row_mask:0xf bank_mask:0x3
	v_mov_b32_dpp v51, v193 row_ror:8 row_mask:0xf bank_mask:0x3
	s_waitcnt vmcnt(24)
	v_mul_f32_e32 v52, v52, v238
	v_mul_f32_e32 v53, v53, v238
	v_mul_f32_e32 v54, v54, v238
	v_mul_f32_e32 v55, v55, v238
	v_mul_f32_e32 v48, v48, v239
	v_mul_f32_e32 v49, v49, v239
	v_mul_f32_e32 v50, v50, v239
	v_mul_f32_e32 v51, v51, v239
	v_fma_f32 v52, v52, v128, v174
	v_fma_f32 v53, v53, v129, v175
	v_fma_f32 v54, v54, v130, v176
	v_fma_f32 v55, v55, v131, v177
	v_fma_f32 v48, v48, v128, v178
	v_fma_f32 v49, v49, v129, v179
	v_fma_f32 v50, v50, v130, v180
	v_fma_f32 v51, v51, v131, v181
	v_add_u32_e32 v252, 0x90000, v157
	v_add_u32_e32 v253, 0x98000, v157
	global_store_dwordx4 v252, v[52:55], s[6:7] nt
	global_store_dwordx4 v253, v[48:51], s[6:7] nt
	v_mov_b32_e32 v190, v36
	v_mov_b32_e32 v191, v37
	v_mov_b32_e32 v192, v38
	v_mov_b32_e32 v193, v39
	v_mov_b32_dpp v36, v32 row_ror:8 row_mask:0xf bank_mask:0xc
	v_mov_b32_dpp v37, v33 row_ror:8 row_mask:0xf bank_mask:0xc
	v_mov_b32_dpp v38, v34 row_ror:8 row_mask:0xf bank_mask:0xc
	v_mov_b32_dpp v39, v35 row_ror:8 row_mask:0xf bank_mask:0xc
	v_mov_b32_dpp v32, v190 row_ror:8 row_mask:0xf bank_mask:0x3
	v_mov_b32_dpp v33, v191 row_ror:8 row_mask:0xf bank_mask:0x3
	v_mov_b32_dpp v34, v192 row_ror:8 row_mask:0xf bank_mask:0x3
	v_mov_b32_dpp v35, v193 row_ror:8 row_mask:0xf bank_mask:0x3
	s_waitcnt vmcnt(22)
	v_mul_f32_e32 v36, v36, v238
	v_mul_f32_e32 v37, v37, v238
	v_mul_f32_e32 v38, v38, v238
	v_mul_f32_e32 v39, v39, v238
	v_mul_f32_e32 v32, v32, v239
	v_mul_f32_e32 v33, v33, v239
	v_mul_f32_e32 v34, v34, v239
	v_mul_f32_e32 v35, v35, v239
	v_fma_f32 v36, v36, v132, v182
	v_fma_f32 v37, v37, v133, v183
	v_fma_f32 v38, v38, v134, v184
	v_fma_f32 v39, v39, v135, v185
	v_fma_f32 v32, v32, v132, v186
	v_fma_f32 v33, v33, v133, v187
	v_fma_f32 v34, v34, v134, v188
	v_fma_f32 v35, v35, v135, v189
	v_add_u32_e32 v252, 0x90000, v157
	v_add_u32_e32 v253, 0x98000, v157
	global_store_dwordx4 v252, v[36:39], s[6:7] offset:512 nt
	global_store_dwordx4 v253, v[32:35], s[6:7] offset:512 nt
	v_mov_b32_e32 v190, v28
	v_mov_b32_e32 v191, v29
	v_mov_b32_e32 v192, v30
	v_mov_b32_e32 v193, v31
	v_mov_b32_dpp v28, v24 row_ror:8 row_mask:0xf bank_mask:0xc
	v_mov_b32_dpp v29, v25 row_ror:8 row_mask:0xf bank_mask:0xc
	v_mov_b32_dpp v30, v26 row_ror:8 row_mask:0xf bank_mask:0xc
	v_mov_b32_dpp v31, v27 row_ror:8 row_mask:0xf bank_mask:0xc
	v_mov_b32_dpp v24, v190 row_ror:8 row_mask:0xf bank_mask:0x3
	v_mov_b32_dpp v25, v191 row_ror:8 row_mask:0xf bank_mask:0x3
	v_mov_b32_dpp v26, v192 row_ror:8 row_mask:0xf bank_mask:0x3
	v_mov_b32_dpp v27, v193 row_ror:8 row_mask:0xf bank_mask:0x3
	s_waitcnt vmcnt(20)
;     __device__ __forceinline__ void fused(f32x4 (&acc)[2][2][4][2], const Unit& u, int wr, int wc, int fr, int fq, PG8_LAS unsigned char* lds, int wid, int lane) const {
;     ...
; #pragma unroll
;         for (int ai = 0; ai < 2; ++ai)
; #pragma unroll
;             for (int m = 0; m < 4; ++m) { const int r = ai * HALF + wr * 64 + m * 16 + fr; const float rs = S[r]; const size_t off = (size_t)(row_off + u.pm * BM + r) * DM + col0;
; #pragma unroll
;                 for (int bj = 0; bj < 2; ++bj)
; #pragma unroll
;                     for (int n = 0; n < 2; ++n) { const f32x4 bs = *(const f32x4*)(base + off + bj * HALF + n * 16); __builtin_nontemporal_store(bs + acc[ai][bj][m][n] * rs * g[bj][n], (f32x4*)(out + off + bj * HALF + n * 16)); }
;                 if (m & 1) asm volatile("" ::: "memory"); }
;         asm volatile("s_waitcnt lgkmcnt(0)" ::: "memory"); __builtin_amdgcn_s_barrier(); asm volatile("" ::: "memory");
	v_mul_f32_e32 v28, v28, v240
	v_mul_f32_e32 v29, v29, v240
	v_mul_f32_e32 v30, v30, v240
	v_mul_f32_e32 v31, v31, v240
	v_mul_f32_e32 v24, v24, v241
	v_mul_f32_e32 v25, v25, v241
	v_mul_f32_e32 v26, v26, v241
	v_mul_f32_e32 v27, v27, v241
	v_fma_f32 v28, v28, v128, v196
	v_fma_f32 v29, v29, v129, v197
	v_fma_f32 v30, v30, v130, v198
	v_fma_f32 v31, v31, v131, v199
	v_fma_f32 v24, v24, v128, v200
	v_fma_f32 v25, v25, v129, v201
	v_fma_f32 v26, v26, v130, v202
	v_fma_f32 v27, v27, v131, v203
	v_add_u32_e32 v252, 0xa0000, v157
	v_add_u32_e32 v253, 0xa8000, v157
	global_store_dwordx4 v252, v[28:31], s[6:7] nt
	global_store_dwordx4 v253, v[24:27], s[6:7] nt
	v_mov_b32_e32 v190, v12
	v_mov_b32_e32 v191, v13
	v_mov_b32_e32 v192, v14
	v_mov_b32_e32 v193, v15
	v_mov_b32_dpp v12, v8 row_ror:8 row_mask:0xf bank_mask:0xc
	v_mov_b32_dpp v13, v9 row_ror:8 row_mask:0xf bank_mask:0xc
	v_mov_b32_dpp v14, v10 row_ror:8 row_mask:0xf bank_mask:0xc
	v_mov_b32_dpp v15, v11 row_ror:8 row_mask:0xf bank_mask:0xc
	v_mov_b32_dpp v8, v190 row_ror:8 row_mask:0xf bank_mask:0x3
	v_mov_b32_dpp v9, v191 row_ror:8 row_mask:0xf bank_mask:0x3
	v_mov_b32_dpp v10, v192 row_ror:8 row_mask:0xf bank_mask:0x3
	v_mov_b32_dpp v11, v193 row_ror:8 row_mask:0xf bank_mask:0x3
	s_waitcnt vmcnt(18)
	v_mul_f32_e32 v12, v12, v240
	v_mul_f32_e32 v13, v13, v240
	v_mul_f32_e32 v14, v14, v240
	v_mul_f32_e32 v15, v15, v240
	v_mul_f32_e32 v8, v8, v241
	v_mul_f32_e32 v9, v9, v241
	v_mul_f32_e32 v10, v10, v241
	v_mul_f32_e32 v11, v11, v241
	v_fma_f32 v12, v12, v132, v204
	v_fma_f32 v13, v13, v133, v205
	v_fma_f32 v14, v14, v134, v206
	v_fma_f32 v15, v15, v135, v207
	v_fma_f32 v8, v8, v132, v208
	v_fma_f32 v9, v9, v133, v209
	v_fma_f32 v10, v10, v134, v210
	v_fma_f32 v11, v11, v135, v211
	v_add_u32_e32 v252, 0xa0000, v157
	v_add_u32_e32 v253, 0xa8000, v157
	global_store_dwordx4 v252, v[12:15], s[6:7] offset:512 nt
	global_store_dwordx4 v253, v[8:11], s[6:7] offset:512 nt
	v_mov_b32_e32 v190, v20
	v_mov_b32_e32 v191, v21
	v_mov_b32_e32 v192, v22
	v_mov_b32_e32 v193, v23
	v_mov_b32_dpp v20, v16 row_ror:8 row_mask:0xf bank_mask:0xc
	v_mov_b32_dpp v21, v17 row_ror:8 row_mask:0xf bank_mask:0xc
	v_mov_b32_dpp v22, v18 row_ror:8 row_mask:0xf bank_mask:0xc
	v_mov_b32_dpp v23, v19 row_ror:8 row_mask:0xf bank_mask:0xc
	v_mov_b32_dpp v16, v190 row_ror:8 row_mask:0xf bank_mask:0x3
	v_mov_b32_dpp v17, v191 row_ror:8 row_mask:0xf bank_mask:0x3
	v_mov_b32_dpp v18, v192 row_ror:8 row_mask:0xf bank_mask:0x3
	v_mov_b32_dpp v19, v193 row_ror:8 row_mask:0xf bank_mask:0x3
	s_waitcnt vmcnt(16)
	v_mul_f32_e32 v20, v20, v242
	v_mul_f32_e32 v21, v21, v242
	v_mul_f32_e32 v22, v22, v242
	v_mul_f32_e32 v23, v23, v242
	v_mul_f32_e32 v16, v16, v243
	v_mul_f32_e32 v17, v17, v243
	v_mul_f32_e32 v18, v18, v243
	v_mul_f32_e32 v19, v19, v243
	v_fma_f32 v20, v20, v128, v212
	v_fma_f32 v21, v21, v129, v213
	v_fma_f32 v22, v22, v130, v214
	v_fma_f32 v23, v23, v131, v215
	v_fma_f32 v16, v16, v128, v216
	v_fma_f32 v17, v17, v129, v217
	v_fma_f32 v18, v18, v130, v218
	v_fma_f32 v19, v19, v131, v219
	v_add_u32_e32 v252, 0xb0000, v157
	v_add_u32_e32 v253, 0xb8000, v157
	global_store_dwordx4 v252, v[20:23], s[6:7] nt
	global_store_dwordx4 v253, v[16:19], s[6:7] nt
	v_mov_b32_e32 v190, v4
	v_mov_b32_e32 v191, v5
	v_mov_b32_e32 v192, v6
	v_mov_b32_e32 v193, v7
	v_mov_b32_dpp v4, v0 row_ror:8 row_mask:0xf bank_mask:0xc
	v_mov_b32_dpp v5, v1 row_ror:8 row_mask:0xf bank_mask:0xc
	v_mov_b32_dpp v6, v2 row_ror:8 row_mask:0xf bank_mask:0xc
	v_mov_b32_dpp v7, v3 row_ror:8 row_mask:0xf bank_mask:0xc
	v_mov_b32_dpp v0, v190 row_ror:8 row_mask:0xf bank_mask:0x3
	v_mov_b32_dpp v1, v191 row_ror:8 row_mask:0xf bank_mask:0x3
	v_mov_b32_dpp v2, v192 row_ror:8 row_mask:0xf bank_mask:0x3
	v_mov_b32_dpp v3, v193 row_ror:8 row_mask:0xf bank_mask:0x3
	s_waitcnt vmcnt(14)
	v_mul_f32_e32 v4, v4, v242
	v_mul_f32_e32 v5, v5, v242
	v_mul_f32_e32 v6, v6, v242
	v_mul_f32_e32 v7, v7, v242
	v_mul_f32_e32 v0, v0, v243
	v_mul_f32_e32 v1, v1, v243
	v_mul_f32_e32 v2, v2, v243
	v_mul_f32_e32 v3, v3, v243
	v_fma_f32 v4, v4, v132, v220
	v_fma_f32 v5, v5, v133, v221
	v_fma_f32 v6, v6, v134, v222
	v_fma_f32 v7, v7, v135, v223
	v_fma_f32 v0, v0, v132, v224
	v_fma_f32 v1, v1, v133, v225
	v_fma_f32 v2, v2, v134, v226
	v_fma_f32 v3, v3, v135, v227
	v_add_u32_e32 v252, 0xb0000, v157
	v_add_u32_e32 v253, 0xb8000, v157
	global_store_dwordx4 v252, v[4:7], s[6:7] offset:512 nt
	global_store_dwordx4 v253, v[0:3], s[6:7] offset:512 nt
	s_waitcnt lgkmcnt(0)
	s_barrier
